# dilated/diff unit start: bias-table load, Q loads and first K/V tile loads overlapped (waits moved to first consumers) on top of opt12
# speedup vs baseline: 1.0087x; 1.0009x over previous
; __device__ __forceinline__ unsigned range_mask(int lo, int hi_incl) { const unsigned up = (hi_incl >= 31) ? 0xffffffffu : ((1u << (hi_incl + 1)) - 1u); return up & ~((1u << lo) - 1u); }
; __device__ __forceinline__ void phase_dilated_mfma(const PT a, unsigned char* ldsb, int tid, int lane, int wave, int bid, int nblk) {
;     ...
;         const int dil = 1 << (2 * g);
;         __syncthreads();
;         if (tid < 129) tab[tid] = biasT[(g * 8 + h) * BT + tid * dil] * LOG2E;
;         const bool act = wave * 32 < nq;
;         const int iq = i0 + ((wave * 32) % nq) + l32, tok = b * SEQ + r + dil * iq;
;         const bf16* base_b = proj + (size_t)b * SEQ * NP;
;         bf16x8 qf[4]; load_qfrag(proj + (size_t)tok * NP + (g * 8 + h) * 64, hi, qf, QSCALE2);
;         f32x16 O[2]; float m = -1e30f, l = 0.f;
; #pragma unroll
;         for (int ds = 0; ds < 2; ++ds)
; #pragma unroll
;             for (int i = 0; i < 16; ++i) O[ds][i] = 0.f;
;         const int wq0 = i0 + wave * 32;
;         attn_pass<64, 2, 8960, true>(range_mask((i0 - 128 > 0 ? i0 - 128 : 0) >> 6, (i0 + nq - 1) >> 6), base_b, r, dil, ((3 + g) * 8 + h) * 64, ((6 + g) * 8 + h) * 64, Ks, Vt, 0, qf, m, l, O, tab, (const unsigned char*)nullptr, iq, 128, 0xffffffffu,
.LBB0_315:
	s_and_b32 s31, s16, 7
	s_lshl_b32 s38, s34, 1
	s_barrier
	s_and_saveexec_b64 s[0:1], s[4:5]
	s_cbranch_execz .LBB0_317
	s_lshl_b32 s2, s34, 3
	s_or_b32 s2, s2, s31
	s_mulk_i32 s2, 0x840
	v_lshlrev_b32_e32 v0, s38, v146
	v_add_u32_e32 v2, s2, v0
	v_ashrrev_i32_e32 v3, 31, v2
	v_lshl_add_u64 v[2:3], v[2:3], 2, s[10:11]
	global_load_dword v108, v[2:3], off
.LBB0_317:
	s_or_b64 exec, exec, s[0:1]
	v_cvt_f32_u32_e32 v0, s19
	s_sub_i32 s0, 0, s19
	v_mov_b64_e32 v[2:3], s[8:9]
	v_mov_b32_e32 v105, v1
	v_rcp_iflag_f32_e32 v0, v0
	s_nop 0
	v_mul_f32_e32 v0, 0x4f7ffffe, v0
	v_cvt_u32_f32_e32 v0, v0
	s_nop 0
	v_readfirstlane_b32 s1, v0
	s_mul_i32 s0, s0, s1
	s_mul_hi_u32 s0, s1, s0
	s_add_i32 s1, s1, s0
	s_mul_hi_u32 s0, s29, s1
	s_mul_i32 s0, s0, s19
	s_sub_i32 s0, s29, s0
	s_sub_i32 s1, s0, s19
	s_cmp_ge_u32 s0, s19
	s_cselect_b32 s0, s1, s0
	s_sub_i32 s1, s0, s19
	s_cmp_ge_u32 s0, s19
	s_cselect_b32 s0, s1, s0
	s_xor_b32 s0, s0, s28
	s_sub_i32 s0, s0, s28
	s_add_i32 s0, s0, s41
	s_lshl_b32 s1, s18, 11
	v_or_b32_e32 v107, s0, v112
	s_or_b32 s1, s1, s35
	v_lshlrev_b32_e32 v0, s38, v107
	s_lshl_b32 s2, s31, 7
	s_lshl_b32 s16, s34, 10
	v_add_u32_e32 v106, s1, v0
	s_or_b32 s90, s16, s2
	v_mad_i64_i32 v[2:3], s[0:1], v106, s76, v[2:3]
	v_lshl_add_u64 v[2:3], v[2:3], 0, s[90:91]
	v_lshl_add_u64 v[2:3], v[2:3], 0, v[104:105]
	global_load_dwordx4 v[14:17], v[2:3], off
	global_load_dwordx4 v[10:13], v[2:3], off offset:32
	global_load_dwordx4 v[6:9], v[2:3], off offset:64
	s_nop 0
	global_load_dwordx4 v[2:5], v[2:3], off offset:96
	s_and_saveexec_b64 s[0:1], s[4:5]
	s_cbranch_execz .Ldil_tab_skip
	s_waitcnt vmcnt(4)
	v_mul_f32_e32 v108, 0x3fb8aa3b, v108
	ds_write_b32 v113, v108 offset:36864
.Ldil_tab_skip:
	s_or_b64 exec, exec, s[0:1]
	s_lshl_b32 s36, s31, 6
	s_cmp_lt_i32 s27, s19
	s_cselect_b64 s[16:17], -1, 0
	s_add_i32 s1, s19, s41
	s_add_i32 s1, s1, -1
	s_max_i32 s0, s41, 0x80
	s_lshr_b32 s2, s1, 6
	s_addk_i32 s0, 0xff80
	s_lshl_b32 s2, 2, s2
	s_lshr_b32 s0, s0, 6
	s_add_i32 s2, s2, -1
	s_cmpk_lt_u32 s1, 0x7c0
	s_cselect_b32 s1, s2, -1
	s_lshl_b32 s0, -1, s0
	s_and_b32 s20, s1, s0
	s_cmp_eq_u32 s20, 0
	s_cbranch_scc0 .Ldil_q_go
	s_waitcnt vmcnt(0)
	s_branch .LBB0_337
.Ldil_q_go:
	s_mul_i32 s0, s18, 0x3e00000
	s_mul_hi_i32 s1, s18, 0x3e00000
	s_add_u32 s0, s8, s0
	s_ff1_i32_b32 s37, s20
	s_addc_u32 s1, s9, s1
	s_lshl_b32 s19, s37, 6
	s_lshl_b32 s19, s19, s38
	s_or_b32 s19, s19, s35
	v_lshlrev_b32_e32 v105, s38, v114
	s_lshl_b32 s2, s34, 9
	v_add_u32_e32 v0, s19, v105
	v_mov_b64_e32 v[18:19], s[0:1]
	v_lshlrev_b32_e32 v119, s38, v103
	s_or_b32 s2, s2, s36
	v_mad_i64_i32 v[18:19], s[42:43], v0, s76, v[18:19]
	v_add_u32_e32 v0, s19, v119
	s_add_i32 s90, s2, 0x600
	v_mul_u32_u24_e32 v0, 0x3e00, v0
	s_add_i32 s18, s2, 0xc00
	v_lshl_add_u64 v[18:19], s[90:91], 1, v[18:19]
	v_lshl_add_u64 v[20:21], v[0:1], 1, s[0:1]
	s_mov_b32 s19, s91
	v_lshl_add_u64 v[18:19], v[98:99], 1, v[18:19]
	v_lshl_add_u64 v[20:21], s[18:19], 1, v[20:21]
	v_lshl_add_u64 v[20:21], v[100:101], 1, v[20:21]
	global_load_dwordx4 v[66:69], v[18:19], off
	global_load_dwordx4 v[70:73], v[20:21], off
	s_add_i32 s21, s20, -1
	s_and_b32 s39, s21, s20
	v_sub_co_u32_e64 v0, s[20:21], s39, 1
	s_nop 0
	v_readfirstlane_b32 s40, v0
	s_ff1_i32_b32 s42, s39
	s_add_i32 s38, s38, 6
	s_and_b64 vcc, exec, s[20:21]
	s_cbranch_vccnz .LBB0_320
	s_lshl_b32 s43, s42, s38
	s_add_i32 s43, s43, s35
	v_add_u32_e32 v0, s43, v105
	v_mov_b64_e32 v[18:19], s[0:1]
	v_mad_i64_i32 v[18:19], s[44:45], v0, s76, v[18:19]
	v_add_u32_e32 v0, s43, v119
	v_mul_lo_u32 v0, v0, s89
	v_lshl_add_u64 v[18:19], s[90:91], 1, v[18:19]
	v_lshl_add_u64 v[20:21], v[0:1], 1, s[0:1]
	v_lshl_add_u64 v[18:19], v[98:99], 1, v[18:19]
	v_lshl_add_u64 v[20:21], s[18:19], 1, v[20:21]
	v_lshl_add_u64 v[20:21], v[100:101], 1, v[20:21]
	global_load_dwordx4 v[74:77], v[18:19], off
	global_load_dwordx4 v[78:81], v[20:21], off
; __device__ __forceinline__ unsigned pkh(float lo, float hi) { f32v2_t v; v.x = lo; v.y = hi; return __builtin_bit_cast(unsigned, __builtin_convertvector(v, bf16v2_t)); }
; __device__ __forceinline__ float bf_lo(unsigned w) { return __uint_as_float(w << 16); }
; __device__ __forceinline__ float bf_hi(unsigned w) { return __uint_as_float(w & 0xffff0000u); }
; __device__ __forceinline__ unsigned range_mask(int lo, int hi_incl) { const unsigned up = (hi_incl >= 31) ? 0xffffffffu : ((1u << (hi_incl + 1)) - 1u); return up & ~((1u << lo) - 1u); }
; __device__ __forceinline__ void load_qfrag(const bf16* qrow, int hi, bf16x8 (&qf)[4], float sc) {
;     u32x4 w0 = *(const u32x4*)(qrow + 0 * 16 + hi * 8), w1 = *(const u32x4*)(qrow + 1 * 16 + hi * 8), w2 = *(const u32x4*)(qrow + 2 * 16 + hi * 8), w3 = *(const u32x4*)(qrow + 3 * 16 + hi * 8);
;     asm volatile("" : "+v"(w0), "+v"(w1), "+v"(w2), "+v"(w3));
;     const u32x4 wv[4] = {w0, w1, w2, w3};
; #pragma unroll
;     for (int c = 0; c < 4; ++c) { const u32x4 w = wv[c]; u32x4 o;
;         o.x = pkh(bf_lo(w.x) * sc, bf_hi(w.x) * sc); o.y = pkh(bf_lo(w.y) * sc, bf_hi(w.y) * sc);
;         o.z = pkh(bf_lo(w.z) * sc, bf_hi(w.z) * sc); o.w = pkh(bf_lo(w.w) * sc, bf_hi(w.w) * sc);
;         qf[c] = __builtin_bit_cast(bf16x8, o); }
; }
; __device__ __forceinline__ void phase_dilated_mfma(const PT a, unsigned char* ldsb, int tid, int lane, int wave, int bid, int nblk) {
;     ...
;         f32x16 O[2]; float m = -1e30f, l = 0.f;
; #pragma unroll
;         for (int ds = 0; ds < 2; ++ds)
; #pragma unroll
;             for (int i = 0; i < 16; ++i) O[ds][i] = 0.f;
;         const int wq0 = i0 + wave * 32;
;         attn_pass<64, 2, 8960, true>(range_mask((i0 - 128 > 0 ? i0 - 128 : 0) >> 6, (i0 + nq - 1) >> 6), base_b, r, dil, ((3 + g) * 8 + h) * 64, ((6 + g) * 8 + h) * 64, Ks, Vt, 0, qf, m, l, O, tab, (const unsigned char*)nullptr, iq, 128, 0xffffffffu,
;                          act ? wq0 + 31 : -1, wq0 - 128, tid, l32, hi);
.LBB0_320:
	s_waitcnt vmcnt(2)
	s_and_b32 s40, s40, s39
	s_and_b64 s[20:21], exec, s[20:21]
	v_lshlrev_b32_e32 v18, 16, v14
	v_and_b32_e32 v19, 0xffff0000, v14
	s_mov_b32 s20, 0x3e38aa3b
	v_lshlrev_b32_e32 v14, 16, v15
	v_and_b32_e32 v15, 0xffff0000, v15
	v_pk_mul_f32 v[14:15], v[14:15], s[20:21] op_sel_hi:[1,0]
	s_cselect_b32 s39, -1, s42
	v_cvt_pk_bf16_f32 v83, v14, v15
	v_lshlrev_b32_e32 v14, 16, v16
	v_and_b32_e32 v15, 0xffff0000, v16
	v_pk_mul_f32 v[14:15], v[14:15], s[20:21] op_sel_hi:[1,0]
	s_add_i32 s42, s41, s27
	v_cvt_pk_bf16_f32 v84, v14, v15
	v_lshlrev_b32_e32 v14, 16, v17
	v_and_b32_e32 v15, 0xffff0000, v17
	v_pk_mul_f32 v[14:15], v[14:15], s[20:21] op_sel_hi:[1,0]
	s_or_b32 s41, s42, 31
	v_cvt_pk_bf16_f32 v85, v14, v15
	v_lshlrev_b32_e32 v14, 16, v10
	v_and_b32_e32 v15, 0xffff0000, v10
	v_lshlrev_b32_e32 v10, 16, v11
	v_and_b32_e32 v11, 0xffff0000, v11
	v_pk_mul_f32 v[10:11], v[10:11], s[20:21] op_sel_hi:[1,0]
	v_pk_mul_f32 v[18:19], v[18:19], s[20:21] op_sel_hi:[1,0]
	v_cvt_pk_bf16_f32 v87, v10, v11
	v_lshlrev_b32_e32 v10, 16, v12
	v_and_b32_e32 v11, 0xffff0000, v12
	v_pk_mul_f32 v[10:11], v[10:11], s[20:21] op_sel_hi:[1,0]
	v_pk_mul_f32 v[14:15], v[14:15], s[20:21] op_sel_hi:[1,0]
	v_cvt_pk_bf16_f32 v88, v10, v11
	v_lshlrev_b32_e32 v10, 16, v13
	v_and_b32_e32 v11, 0xffff0000, v13
	v_pk_mul_f32 v[10:11], v[10:11], s[20:21] op_sel_hi:[1,0]
	v_mov_b32_e32 v120, 0
	v_cvt_pk_bf16_f32 v89, v10, v11
	v_lshlrev_b32_e32 v10, 16, v6
	v_and_b32_e32 v11, 0xffff0000, v6
	v_lshlrev_b32_e32 v6, 16, v7
	v_and_b32_e32 v7, 0xffff0000, v7
	v_pk_mul_f32 v[6:7], v[6:7], s[20:21] op_sel_hi:[1,0]
	v_pk_mul_f32 v[10:11], v[10:11], s[20:21] op_sel_hi:[1,0]
	v_cvt_pk_bf16_f32 v91, v6, v7
	v_lshlrev_b32_e32 v6, 16, v8
	v_and_b32_e32 v7, 0xffff0000, v8
	v_pk_mul_f32 v[6:7], v[6:7], s[20:21] op_sel_hi:[1,0]
	v_cvt_pk_bf16_f32 v82, v18, v19
	v_cvt_pk_bf16_f32 v92, v6, v7
	v_lshlrev_b32_e32 v6, 16, v9
	v_and_b32_e32 v7, 0xffff0000, v9
	v_pk_mul_f32 v[6:7], v[6:7], s[20:21] op_sel_hi:[1,0]
	v_cvt_pk_bf16_f32 v86, v14, v15
	v_cvt_pk_bf16_f32 v93, v6, v7
	v_lshlrev_b32_e32 v6, 16, v2
	v_and_b32_e32 v7, 0xffff0000, v2
	v_lshlrev_b32_e32 v2, 16, v3
	v_and_b32_e32 v3, 0xffff0000, v3
	v_pk_mul_f32 v[2:3], v[2:3], s[20:21] op_sel_hi:[1,0]
	v_pk_mul_f32 v[6:7], v[6:7], s[20:21] op_sel_hi:[1,0]
	v_cvt_pk_bf16_f32 v95, v2, v3
	v_lshlrev_b32_e32 v2, 16, v4
	v_and_b32_e32 v3, 0xffff0000, v4
	v_pk_mul_f32 v[2:3], v[2:3], s[20:21] op_sel_hi:[1,0]
	v_cvt_pk_bf16_f32 v90, v10, v11
	v_cvt_pk_bf16_f32 v96, v2, v3
	v_lshlrev_b32_e32 v2, 16, v5
	v_and_b32_e32 v3, 0xffff0000, v5
	v_pk_mul_f32 v[2:3], v[2:3], s[20:21] op_sel_hi:[1,0]
	s_and_b64 s[20:21], s[16:17], exec
	s_cselect_b32 s41, s41, -1
	s_addk_i32 s42, 0xff80
	s_lshl_b64 s[20:21], s[90:91], 1
	s_add_u32 s20, s0, s20
	s_addc_u32 s21, s1, s21
	s_lshl_b64 s[18:19], s[18:19], 1
	s_add_u32 s0, s0, s18
	s_addc_u32 s1, s1, s19
	v_cvt_pk_bf16_f32 v94, v6, v7
	v_cvt_pk_bf16_f32 v97, v2, v3
	v_lshl_add_u64 v[108:109], v[98:99], 1, s[20:21]
	v_lshl_add_u64 v[110:111], v[100:101], 1, s[0:1]
	v_mov_b32_e32 v121, 0xf149f2ca
	v_mov_b32_e32 v18, 0
	v_mov_b32_e32 v19, v120
	v_mov_b32_e32 v20, v120
	v_mov_b32_e32 v21, v120
	v_mov_b32_e32 v22, v120
	v_mov_b32_e32 v23, v120
	v_mov_b32_e32 v24, v120
	v_mov_b32_e32 v25, v120
	v_mov_b32_e32 v26, v120
	v_mov_b32_e32 v27, v120
	v_mov_b32_e32 v28, v120
	v_mov_b32_e32 v29, v120
	v_mov_b32_e32 v30, v120
	v_mov_b32_e32 v31, v120
	v_mov_b32_e32 v32, v120
	v_mov_b32_e32 v33, v120
	v_mov_b32_e32 v2, 0
	v_mov_b32_e32 v3, v120
	v_mov_b32_e32 v4, v120
	v_mov_b32_e32 v5, v120
	v_mov_b32_e32 v6, v120
	v_mov_b32_e32 v7, v120
	v_mov_b32_e32 v8, v120
	v_mov_b32_e32 v9, v120
	v_mov_b32_e32 v10, v120
	v_mov_b32_e32 v11, v120
	v_mov_b32_e32 v12, v120
	v_mov_b32_e32 v13, v120
	v_mov_b32_e32 v14, v120
	v_mov_b32_e32 v15, v120
	v_mov_b32_e32 v16, v120
	v_mov_b32_e32 v17, v120

; __device__ __forceinline__ unsigned range_mask(int lo, int hi_incl) { const unsigned up = (hi_incl >= 31) ? 0xffffffffu : ((1u << (hi_incl + 1)) - 1u); return up & ~((1u << lo) - 1u); }
; __device__ __forceinline__ void phase_diff_mfma(const PT a, int lyr, unsigned char* ldsb, int tid, int lane, int wave, int bid, int nblk) {
;     ...
;         const int bh = u & 31, b = bh >> 3, h = bh & 7, qt = u < 256 ? 15 - (u >> 5) : ((u - 256) >> 5);
;         if (h != hcur) { __syncthreads(); for (int i = tid; i < 2048; i += 512) { tab[i] = biasT[(40 + h) * BT + i] * LOG2E; bk[i] = (unsigned char)t5_bucket(i); } hcur = h; }
;         const int t0 = qt * 128, tq = t0 + wq * 32 + l32, tok = b * SEQ + tq;
;         const bf16* base_b = proj + (size_t)b * SEQ * NP;
;         bf16x8 qf[4]; load_qfrag(proj + (size_t)tok * NP + OFF_CQ + (h * 2 + mp) * 64, hi, qf, QSCALE2);
;         f32x16 O[4]; float m = -1e30f, l = 0.f;
; #pragma unroll
;         for (int ds = 0; ds < 4; ++ds)
; #pragma unroll
;             for (int i = 0; i < 16; ++i) O[ds][i] = 0.f;
;         attn_pass<128, 4, 17408, false>(range_mask(0, (t0 + 127) >> 6), base_b, 0, 1, OFF_CK + h * 128, OFF_CV + h * 128, Ks, Vt, mp * 64, qf, m, l, O, tab, bk, tq, 1 << 20, 0xffffffffu, t0 + wq * 32 + 31, -(1 << 20), tid, l32, hi);
.LBB0_355:
	s_lshr_b32 s0, s70, 5
	s_add_i32 s1, s70, 0xffffff00
	s_bfe_u32 s6, s70, 0x20003
	s_sub_i32 s0, 15, s0
	s_lshr_b32 s1, s1, 5
	s_cmpk_lt_i32 s70, 0x100
	s_cselect_b32 s0, s0, s1
	s_lshl_b32 s8, s0, 7
	s_or_b32 s5, s8, s81
	v_readlane_b32 s10, v253, 40
	v_or_b32_e32 v244, s5, v192
	v_readlane_b32 s11, v253, 41
	v_lshl_add_u32 v166, s6, 11, v244
	s_lshl_b32 s4, s2, 7
	v_mov_b64_e32 v[2:3], s[10:11]
	v_mad_u64_u32 v[2:3], s[0:1], v166, s76, v[2:3]
	v_readlane_b32 s0, v253, 44
	s_add_i32 s0, s4, s0
	s_ashr_i32 s1, s0, 31
	v_lshl_add_u64 v[2:3], s[0:1], 1, v[2:3]
	v_mov_b32_e32 v159, v1
	v_lshl_add_u64 v[2:3], v[2:3], 0, v[158:159]
	s_mov_b64 s[0:1], 0x3260
	v_lshl_add_u64 v[14:15], v[2:3], 0, s[0:1]
	s_movk_i32 s0, 0x3000
	v_add_co_u32_e32 v10, vcc, s0, v2
	s_mul_i32 s6, s6, 0x3e00000
	s_nop 0
	v_addc_co_u32_e32 v11, vcc, 0, v3, vcc
	global_load_dwordx4 v[2:5], v[14:15], off offset:32
	global_load_dwordx4 v[6:9], v[14:15], off offset:64
	s_nop 0
	global_load_dwordx4 v[10:13], v[10:11], off offset:608
	s_nop 0
	global_load_dwordx4 v[14:17], v[14:15], off offset:96
	s_add_u32 s6, s10, s6
	s_addc_u32 s7, s11, 0
	s_lshr_b32 s1, s8, 6
	s_lshl_b32 s1, 4, s1
	s_add_i32 s1, s1, -1
	s_cmpk_lt_u32 s8, 0x741
	s_cselect_b32 s1, s1, -1
	s_add_i32 s8, s1, -1
	s_lshl_b32 s2, s2, 8
	s_or_b32 s94, s5, 31
	s_and_b32 s1, s8, s1
	s_add_u32 s8, s6, s2
	v_mov_b32_e32 v165, v1
	s_addc_u32 s9, s7, 0
	v_lshl_add_u64 v[18:19], s[6:7], 0, v[164:165]
	s_add_u32 s6, s8, 0x3a60
	s_addc_u32 s7, s9, 0
	s_add_i32 s90, s2, 0x4260
	v_lshl_add_u64 v[20:21], s[6:7], 0, v[148:149]
	v_lshl_add_u64 v[22:23], s[6:7], 0, v[150:151]
	v_lshl_add_u64 v[18:19], v[18:19], 0, s[90:91]
	v_lshl_add_u64 v[20:21], v[20:21], 0, v[160:161]
	v_lshl_add_u64 v[22:23], v[22:23], 0, v[162:163]
	v_lshl_add_u64 v[24:25], v[152:153], 1, v[18:19]
	v_lshl_add_u64 v[18:19], v[154:155], 1, v[18:19]
	s_mov_b32 s2, 0x3e38aa3b
	s_mov_b32 s0, 0
	s_add_u32 s82, s8, 0x4260
	v_mov_b32_e32 v0, v1
	v_lshl_add_u64 v[168:169], s[6:7], 0, v[160:161]
	v_lshl_add_u64 v[170:171], s[6:7], 0, v[162:163]
	s_addc_u32 s83, s9, 0
	v_mov_b32_e32 v159, 0
	v_mov_b32_e32 v245, 0xf149f2ca
	global_load_dwordx4 v[112:115], v[20:21], off
	global_load_dwordx4 v[116:119], v[22:23], off
	global_load_dwordx4 v[124:127], v[24:25], off
	global_load_dwordx4 v[132:135], v[18:19], off
	s_waitcnt vmcnt(4)
	v_lshlrev_b32_e32 v18, 16, v10
	v_and_b32_e32 v19, 0xffff0000, v10
	v_lshlrev_b32_e32 v10, 16, v11
	v_and_b32_e32 v11, 0xffff0000, v11
	v_lshlrev_b32_e32 v20, 16, v12
	v_and_b32_e32 v21, 0xffff0000, v12
	v_lshlrev_b32_e32 v12, 16, v13
	v_pk_mul_f32 v[10:11], v[10:11], s[2:3] op_sel_hi:[1,0]
	v_and_b32_e32 v13, 0xffff0000, v13
	v_cvt_pk_bf16_f32 v121, v10, v11
	v_pk_mul_f32 v[10:11], v[12:13], s[2:3] op_sel_hi:[1,0]
	v_pk_mul_f32 v[18:19], v[18:19], s[2:3] op_sel_hi:[1,0]
	v_cvt_pk_bf16_f32 v123, v10, v11
	v_lshlrev_b32_e32 v10, 16, v2
	v_and_b32_e32 v11, 0xffff0000, v2
	v_lshlrev_b32_e32 v2, 16, v3
	v_and_b32_e32 v3, 0xffff0000, v3
	v_pk_mul_f32 v[2:3], v[2:3], s[2:3] op_sel_hi:[1,0]
	v_pk_mul_f32 v[20:21], v[20:21], s[2:3] op_sel_hi:[1,0]
	v_cvt_pk_bf16_f32 v129, v2, v3
	v_lshlrev_b32_e32 v2, 16, v4
	v_and_b32_e32 v3, 0xffff0000, v4
	v_pk_mul_f32 v[2:3], v[2:3], s[2:3] op_sel_hi:[1,0]
	v_pk_mul_f32 v[10:11], v[10:11], s[2:3] op_sel_hi:[1,0]
	v_cvt_pk_bf16_f32 v130, v2, v3
	v_lshlrev_b32_e32 v2, 16, v5
	v_and_b32_e32 v3, 0xffff0000, v5
	v_pk_mul_f32 v[2:3], v[2:3], s[2:3] op_sel_hi:[1,0]
	v_cvt_pk_bf16_f32 v120, v18, v19
	v_cvt_pk_bf16_f32 v131, v2, v3
	v_lshlrev_b32_e32 v2, 16, v6
	v_and_b32_e32 v3, 0xffff0000, v6
	v_pk_mul_f32 v[2:3], v[2:3], s[2:3] op_sel_hi:[1,0]
	v_cvt_pk_bf16_f32 v122, v20, v21
	v_cvt_pk_bf16_f32 v136, v2, v3
	v_lshlrev_b32_e32 v2, 16, v7
	v_and_b32_e32 v3, 0xffff0000, v7
	v_pk_mul_f32 v[2:3], v[2:3], s[2:3] op_sel_hi:[1,0]
	v_cvt_pk_bf16_f32 v128, v10, v11
	v_cvt_pk_bf16_f32 v137, v2, v3
	v_lshlrev_b32_e32 v2, 16, v8
	v_and_b32_e32 v3, 0xffff0000, v8
	v_pk_mul_f32 v[2:3], v[2:3], s[2:3] op_sel_hi:[1,0]
	v_mov_b32_e32 v4, v1
	v_cvt_pk_bf16_f32 v138, v2, v3
	v_lshlrev_b32_e32 v2, 16, v9
	v_and_b32_e32 v3, 0xffff0000, v9
	v_pk_mul_f32 v[2:3], v[2:3], s[2:3] op_sel_hi:[1,0]
	v_mov_b32_e32 v5, v1
	v_cvt_pk_bf16_f32 v139, v2, v3
	v_lshlrev_b32_e32 v2, 16, v14
	v_and_b32_e32 v3, 0xffff0000, v14
	v_pk_mul_f32 v[2:3], v[2:3], s[2:3] op_sel_hi:[1,0]
	v_mov_b32_e32 v14, v1
	v_cvt_pk_bf16_f32 v140, v2, v3
	v_lshlrev_b32_e32 v2, 16, v15
	v_and_b32_e32 v3, 0xffff0000, v15
	v_pk_mul_f32 v[2:3], v[2:3], s[2:3] op_sel_hi:[1,0]
	v_mov_b32_e32 v15, v1
	v_cvt_pk_bf16_f32 v141, v2, v3
	v_lshlrev_b32_e32 v2, 16, v16
	v_and_b32_e32 v3, 0xffff0000, v16
	v_pk_mul_f32 v[2:3], v[2:3], s[2:3] op_sel_hi:[1,0]
	v_mov_b32_e32 v6, v1
	v_cvt_pk_bf16_f32 v142, v2, v3
	v_lshlrev_b32_e32 v2, 16, v17
	v_and_b32_e32 v3, 0xffff0000, v17
	v_pk_mul_f32 v[2:3], v[2:3], s[2:3] op_sel_hi:[1,0]
	v_mov_b32_e32 v7, v1
	v_cvt_pk_bf16_f32 v143, v2, v3
	v_mov_b32_e32 v2, v1
	v_mov_b32_e32 v3, v1
	v_mov_b32_e32 v8, v1
	v_mov_b32_e32 v9, v1
	v_mov_b32_e32 v10, v1
	v_mov_b32_e32 v11, v1
	v_mov_b32_e32 v12, v1
	v_mov_b32_e32 v13, v1
	v_mov_b64_e32 v[30:31], v[14:15]
	v_mov_b64_e32 v[46:47], v[14:15]
	v_mov_b64_e32 v[62:63], v[14:15]
	v_mov_b64_e32 v[78:79], v[14:15]
	v_mov_b64_e32 v[28:29], v[12:13]
	v_mov_b64_e32 v[26:27], v[10:11]
	v_mov_b64_e32 v[24:25], v[8:9]
	v_mov_b64_e32 v[22:23], v[6:7]
	v_mov_b64_e32 v[20:21], v[4:5]
	v_mov_b64_e32 v[18:19], v[2:3]
	v_mov_b64_e32 v[16:17], v[0:1]
	v_mov_b64_e32 v[44:45], v[12:13]
	v_mov_b64_e32 v[42:43], v[10:11]
	v_mov_b64_e32 v[40:41], v[8:9]
	v_mov_b64_e32 v[38:39], v[6:7]
	v_mov_b64_e32 v[36:37], v[4:5]
	v_mov_b64_e32 v[34:35], v[2:3]
	v_mov_b64_e32 v[32:33], v[0:1]
	v_mov_b64_e32 v[60:61], v[12:13]
	v_mov_b64_e32 v[58:59], v[10:11]
	v_mov_b64_e32 v[56:57], v[8:9]
	v_mov_b64_e32 v[54:55], v[6:7]
	v_mov_b64_e32 v[52:53], v[4:5]
	v_mov_b64_e32 v[50:51], v[2:3]
	v_mov_b64_e32 v[48:49], v[0:1]
	v_mov_b64_e32 v[76:77], v[12:13]
	v_mov_b64_e32 v[74:75], v[10:11]
	v_mov_b64_e32 v[72:73], v[8:9]
	v_mov_b64_e32 v[70:71], v[6:7]
	v_mov_b64_e32 v[68:69], v[4:5]
	v_mov_b64_e32 v[66:67], v[2:3]
	v_mov_b64_e32 v[64:65], v[0:1]
	s_mov_b32 s2, s0
	s_branch .LBB0_358
